# v85 + KVQ epilogue row-statistic loads hoisted to tile start (no load round trip at each P6 tile end)
# speedup vs baseline: 1.0026x; 1.0026x over previous
.LBB0_798:
	s_ashr_i32 s29, s28, 31
	s_lshl_b64 s[30:31], s[28:29], 19
	s_add_u32 s30, s96, s30
	s_addc_u32 s31, s97, s31
	s_and_b64 s[34:35], s[4:5], exec
	s_cselect_b32 s3, s31, s1
	s_cselect_b32 s7, s30, s0
	s_ashr_i32 s27, s26, 31
	s_lshl_b64 s[34:35], s[26:27], 19
	s_add_u32 s34, s58, s34
	s_addc_u32 s35, s59, s35
	s_and_b64 s[36:37], s[4:5], exec
	s_cselect_b32 s27, s35, s9
	s_cselect_b32 s29, s34, s8
	s_add_u32 s0, s0, 0x40080
	s_addc_u32 s1, s1, 0
	s_add_u32 s33, s8, 0x100
	s_addc_u32 s38, s9, 0
	s_mov_b32 s39, -2
	s_lshl_b32 s98, s2, 8
	s_add_i32 s98, s98, s67
	v_or_b32_e32 v248, s98, v170
	v_ashrrev_i32_e32 v249, 31, v248
	v_lshl_add_u64 v[248:249], v[248:249], 2, s[10:11]
	global_load_dword v240, v[248:249], off
	global_load_dword v241, v[248:249], off offset:64
	global_load_dword v242, v[248:249], off offset:128
	global_load_dword v243, v[248:249], off offset:192
	global_load_dword v244, v[248:249], off offset:512
	global_load_dword v245, v[248:249], off offset:576
	global_load_dword v246, v[248:249], off offset:640
	global_load_dword v247, v[248:249], off offset:704
	ds_read_b128 v[128:131], v177
	ds_read_b128 v[154:157], v177 offset:1024
	ds_read_b128 v[162:165], v177 offset:2048
	ds_read_b128 v[166:169], v177 offset:3072
	ds_read_b128 v[182:185], v178
	ds_read_b128 v[186:189], v178 offset:1024
	ds_read_b128 v[190:193], v178 offset:2048
	ds_read_b128 v[194:197], v178 offset:3072
	s_add_u32 s8, s0, 0xfffc0080
	s_addc_u32 s9, s1, -1
	s_cmp_eq_u32 s39, 12
	s_cselect_b32 s37, s3, s9
	s_cselect_b32 s36, s7, s8
	s_cselect_b32 s9, s27, s38
	s_cselect_b32 s8, s29, s33
	v_lshl_add_u64 v[158:159], s[0:1], 0, v[146:147]
	s_add_i32 m0, s62, 0xc000
	ds_read_b128 v[198:201], v179
	ds_read_b128 v[202:205], v179 offset:1024
	ds_read_b128 v[206:209], v179 offset:2048
	ds_read_b128 v[210:213], v179 offset:3072
	ds_read_b128 v[214:217], v179 offset:4096
	ds_read_b128 v[218:221], v179 offset:5120
	ds_read_b128 v[222:225], v179 offset:6144
	ds_read_b128 v[226:229], v179 offset:7168
	global_load_lds_dwordx4 v[158:159], off
	s_add_i32 m0, s62, 0xe000
	v_lshl_add_u64 v[158:159], s[0:1], 0, v[148:149]
	global_load_lds_dwordx4 v[158:159], off
	s_waitcnt vmcnt(8) lgkmcnt(0)
	s_barrier
	v_mfma_f32_16x16x32_bf16 v[124:127], v[128:131], v[198:201], 0
	v_mfma_f32_16x16x32_bf16 v[120:123], v[162:165], v[198:201], 0
	v_mfma_f32_16x16x32_bf16 v[108:111], v[128:131], v[206:209], 0
	v_mfma_f32_16x16x32_bf16 v[104:107], v[162:165], v[206:209], 0
	v_mfma_f32_16x16x32_bf16 v[92:95], v[128:131], v[214:217], 0
	v_mfma_f32_16x16x32_bf16 v[88:91], v[162:165], v[214:217], 0
	v_mfma_f32_16x16x32_bf16 v[76:79], v[128:131], v[222:225], 0
	v_mfma_f32_16x16x32_bf16 v[72:75], v[162:165], v[222:225], 0
	v_mfma_f32_16x16x32_bf16 v[124:127], v[154:157], v[202:205], v[124:127]
	v_mfma_f32_16x16x32_bf16 v[120:123], v[166:169], v[202:205], v[120:123]
	v_mfma_f32_16x16x32_bf16 v[108:111], v[154:157], v[210:213], v[108:111]
	v_mfma_f32_16x16x32_bf16 v[104:107], v[166:169], v[210:213], v[104:107]
	v_mfma_f32_16x16x32_bf16 v[92:95], v[154:157], v[218:221], v[92:95]
	v_mfma_f32_16x16x32_bf16 v[88:91], v[166:169], v[218:221], v[88:91]
	v_mfma_f32_16x16x32_bf16 v[76:79], v[154:157], v[226:229], v[76:79]
	v_mfma_f32_16x16x32_bf16 v[72:75], v[166:169], v[226:229], v[72:75]
	v_mfma_f32_16x16x32_bf16 v[116:119], v[182:185], v[198:201], 0
	v_mfma_f32_16x16x32_bf16 v[112:115], v[190:193], v[198:201], 0
	v_mfma_f32_16x16x32_bf16 v[100:103], v[182:185], v[206:209], 0
	v_mfma_f32_16x16x32_bf16 v[96:99], v[190:193], v[206:209], 0
	v_mfma_f32_16x16x32_bf16 v[84:87], v[182:185], v[214:217], 0
	v_mfma_f32_16x16x32_bf16 v[80:83], v[190:193], v[214:217], 0
	v_mfma_f32_16x16x32_bf16 v[68:71], v[182:185], v[222:225], 0
	v_mfma_f32_16x16x32_bf16 v[64:67], v[190:193], v[222:225], 0
	v_mfma_f32_16x16x32_bf16 v[116:119], v[186:189], v[202:205], v[116:119]
	v_mfma_f32_16x16x32_bf16 v[112:115], v[194:197], v[202:205], v[112:115]
	v_mfma_f32_16x16x32_bf16 v[100:103], v[186:189], v[210:213], v[100:103]
	v_mfma_f32_16x16x32_bf16 v[96:99], v[194:197], v[210:213], v[96:99]
	v_mfma_f32_16x16x32_bf16 v[84:87], v[186:189], v[218:221], v[84:87]
	v_mfma_f32_16x16x32_bf16 v[80:83], v[194:197], v[218:221], v[80:83]
	v_mfma_f32_16x16x32_bf16 v[68:71], v[186:189], v[226:229], v[68:71]
	v_mfma_f32_16x16x32_bf16 v[64:67], v[194:197], v[226:229], v[64:67]
	s_barrier
	s_add_i32 s40, s78, s61
	v_lshl_add_u64 v[158:159], s[8:9], 0, v[134:135]
	s_mov_b32 m0, s40
	ds_read_b128 v[198:201], v179 offset:16384
	ds_read_b128 v[202:205], v179 offset:17408
	ds_read_b128 v[206:209], v179 offset:18432
	ds_read_b128 v[210:213], v179 offset:19456
	ds_read_b128 v[214:217], v179 offset:20480
	ds_read_b128 v[218:221], v179 offset:21504
	ds_read_b128 v[222:225], v179 offset:22528
	ds_read_b128 v[226:229], v179 offset:23552
	global_load_lds_dwordx4 v[158:159], off
	s_add_i32 m0, s40, 0x2000
	s_add_u32 s40, s8, 0x40000
	v_lshl_add_u64 v[230:231], s[8:9], 0, v[138:139]
	s_addc_u32 s41, s9, 0
	s_add_i32 s42, s79, s61
	global_load_lds_dwordx4 v[230:231], off
	v_lshl_add_u64 v[232:233], s[40:41], 0, v[134:135]
	s_mov_b32 m0, s42
	v_lshl_add_u64 v[234:235], s[36:37], 0, v[136:137]
	global_load_lds_dwordx4 v[232:233], off
	s_add_i32 m0, s42, 0x2000
	v_lshl_add_u64 v[232:233], s[40:41], 0, v[138:139]
	global_load_lds_dwordx4 v[232:233], off
	s_mov_b32 m0, s62
	v_lshl_add_u64 v[232:233], s[36:37], 0, v[132:133]
	global_load_lds_dwordx4 v[232:233], off
	s_mov_b32 m0, s63
	s_nop 0
	global_load_lds_dwordx4 v[234:235], off
	s_waitcnt vmcnt(8) lgkmcnt(0)
	s_barrier
	v_mfma_f32_16x16x32_bf16 v[60:63], v[128:131], v[198:201], 0
	v_mfma_f32_16x16x32_bf16 v[56:59], v[162:165], v[198:201], 0
	v_mfma_f32_16x16x32_bf16 v[44:47], v[128:131], v[206:209], 0
	v_mfma_f32_16x16x32_bf16 v[40:43], v[162:165], v[206:209], 0
	v_mfma_f32_16x16x32_bf16 v[28:31], v[128:131], v[214:217], 0
	v_mfma_f32_16x16x32_bf16 v[24:27], v[162:165], v[214:217], 0
	v_mfma_f32_16x16x32_bf16 v[12:15], v[128:131], v[222:225], 0
	v_mfma_f32_16x16x32_bf16 v[8:11], v[162:165], v[222:225], 0
	v_mfma_f32_16x16x32_bf16 v[60:63], v[154:157], v[202:205], v[60:63]
	v_mfma_f32_16x16x32_bf16 v[56:59], v[166:169], v[202:205], v[56:59]
	v_mfma_f32_16x16x32_bf16 v[44:47], v[154:157], v[210:213], v[44:47]
	v_mfma_f32_16x16x32_bf16 v[40:43], v[166:169], v[210:213], v[40:43]
	v_mfma_f32_16x16x32_bf16 v[28:31], v[154:157], v[218:221], v[28:31]
	v_mfma_f32_16x16x32_bf16 v[24:27], v[166:169], v[218:221], v[24:27]
	v_mfma_f32_16x16x32_bf16 v[12:15], v[154:157], v[226:229], v[12:15]
	v_mfma_f32_16x16x32_bf16 v[8:11], v[166:169], v[226:229], v[8:11]
	v_mfma_f32_16x16x32_bf16 v[52:55], v[182:185], v[198:201], 0
	v_mfma_f32_16x16x32_bf16 v[48:51], v[190:193], v[198:201], 0
	v_mfma_f32_16x16x32_bf16 v[36:39], v[182:185], v[206:209], 0
	v_mfma_f32_16x16x32_bf16 v[32:35], v[190:193], v[206:209], 0
	v_mfma_f32_16x16x32_bf16 v[20:23], v[182:185], v[214:217], 0
	v_mfma_f32_16x16x32_bf16 v[16:19], v[190:193], v[214:217], 0
	v_mfma_f32_16x16x32_bf16 v[4:7], v[182:185], v[222:225], 0
	v_mfma_f32_16x16x32_bf16 v[0:3], v[190:193], v[222:225], 0
	v_mfma_f32_16x16x32_bf16 v[52:55], v[186:189], v[202:205], v[52:55]
	v_mfma_f32_16x16x32_bf16 v[48:51], v[194:197], v[202:205], v[48:51]
	v_mfma_f32_16x16x32_bf16 v[36:39], v[186:189], v[210:213], v[36:39]
	v_mfma_f32_16x16x32_bf16 v[32:35], v[194:197], v[210:213], v[32:35]
	v_mfma_f32_16x16x32_bf16 v[20:23], v[186:189], v[218:221], v[20:23]
	v_mfma_f32_16x16x32_bf16 v[16:19], v[194:197], v[218:221], v[16:19]
	v_mfma_f32_16x16x32_bf16 v[4:7], v[186:189], v[226:229], v[4:7]
	v_mfma_f32_16x16x32_bf16 v[0:3], v[194:197], v[226:229], v[0:3]
	s_barrier
	s_add_i32 s40, 0, 0x18000
	v_add_u32_e32 v140, s40, v171
	s_add_i32 s41, 0, 0x1c000
	ds_read_b128 v[128:131], v140
	ds_read_b128 v[154:157], v140 offset:1024
	ds_read_b128 v[162:165], v140 offset:2048
	ds_read_b128 v[166:169], v140 offset:3072
	v_add_u32_e32 v140, s41, v171
	ds_read_b128 v[182:185], v140
	ds_read_b128 v[186:189], v140 offset:1024
	ds_read_b128 v[190:193], v140 offset:2048
	ds_read_b128 v[194:197], v140 offset:3072
	s_add_u32 s36, s36, 0x40000
	s_addc_u32 s37, s37, 0
	s_mov_b32 m0, s64
	v_lshl_add_u64 v[236:237], s[36:37], 0, v[132:133]
	ds_read_b128 v[198:201], v179 offset:32768
	ds_read_b128 v[202:205], v179 offset:33792
	ds_read_b128 v[206:209], v179 offset:34816
	ds_read_b128 v[210:213], v179 offset:35840
	ds_read_b128 v[214:217], v179 offset:36864
	ds_read_b128 v[218:221], v179 offset:37888
	ds_read_b128 v[222:225], v179 offset:38912
	ds_read_b128 v[226:229], v179 offset:39936
	global_load_lds_dwordx4 v[236:237], off
	s_mov_b32 m0, s65
	v_lshl_add_u64 v[236:237], s[36:37], 0, v[136:137]
	global_load_lds_dwordx4 v[236:237], off
	s_waitcnt vmcnt(8) lgkmcnt(0)
	s_barrier
	v_mfma_f32_16x16x32_bf16 v[124:127], v[128:131], v[198:201], v[124:127]
	v_mfma_f32_16x16x32_bf16 v[120:123], v[162:165], v[198:201], v[120:123]
	v_mfma_f32_16x16x32_bf16 v[108:111], v[128:131], v[206:209], v[108:111]
	v_mfma_f32_16x16x32_bf16 v[104:107], v[162:165], v[206:209], v[104:107]
	v_mfma_f32_16x16x32_bf16 v[92:95], v[128:131], v[214:217], v[92:95]
	v_mfma_f32_16x16x32_bf16 v[88:91], v[162:165], v[214:217], v[88:91]
	v_mfma_f32_16x16x32_bf16 v[76:79], v[128:131], v[222:225], v[76:79]
	v_mfma_f32_16x16x32_bf16 v[72:75], v[162:165], v[222:225], v[72:75]
	v_mfma_f32_16x16x32_bf16 v[124:127], v[154:157], v[202:205], v[124:127]
	v_mfma_f32_16x16x32_bf16 v[120:123], v[166:169], v[202:205], v[120:123]
	v_mfma_f32_16x16x32_bf16 v[108:111], v[154:157], v[210:213], v[108:111]
	v_mfma_f32_16x16x32_bf16 v[104:107], v[166:169], v[210:213], v[104:107]
	v_mfma_f32_16x16x32_bf16 v[92:95], v[154:157], v[218:221], v[92:95]
	v_mfma_f32_16x16x32_bf16 v[88:91], v[166:169], v[218:221], v[88:91]
	v_mfma_f32_16x16x32_bf16 v[76:79], v[154:157], v[226:229], v[76:79]
	v_mfma_f32_16x16x32_bf16 v[72:75], v[166:169], v[226:229], v[72:75]
	v_mfma_f32_16x16x32_bf16 v[116:119], v[182:185], v[198:201], v[116:119]
	v_mfma_f32_16x16x32_bf16 v[112:115], v[190:193], v[198:201], v[112:115]
	v_mfma_f32_16x16x32_bf16 v[100:103], v[182:185], v[206:209], v[100:103]
	v_mfma_f32_16x16x32_bf16 v[96:99], v[190:193], v[206:209], v[96:99]
	v_mfma_f32_16x16x32_bf16 v[84:87], v[182:185], v[214:217], v[84:87]
	v_mfma_f32_16x16x32_bf16 v[80:83], v[190:193], v[214:217], v[80:83]
	v_mfma_f32_16x16x32_bf16 v[68:71], v[182:185], v[222:225], v[68:71]
	v_mfma_f32_16x16x32_bf16 v[64:67], v[190:193], v[222:225], v[64:67]
	v_mfma_f32_16x16x32_bf16 v[116:119], v[186:189], v[202:205], v[116:119]
	v_mfma_f32_16x16x32_bf16 v[112:115], v[194:197], v[202:205], v[112:115]
	v_mfma_f32_16x16x32_bf16 v[100:103], v[186:189], v[210:213], v[100:103]
	v_mfma_f32_16x16x32_bf16 v[96:99], v[194:197], v[210:213], v[96:99]
	v_mfma_f32_16x16x32_bf16 v[84:87], v[186:189], v[218:221], v[84:87]
	v_mfma_f32_16x16x32_bf16 v[80:83], v[194:197], v[218:221], v[80:83]
	v_mfma_f32_16x16x32_bf16 v[68:71], v[186:189], v[226:229], v[68:71]
	v_mfma_f32_16x16x32_bf16 v[64:67], v[194:197], v[226:229], v[64:67]
	s_barrier
	s_add_i32 s36, s40, s61
	v_lshl_add_u64 v[158:159], v[158:159], 0, s[14:15]
	s_mov_b32 m0, s36
	ds_read_b128 v[198:201], v179 offset:49152
	ds_read_b128 v[202:205], v179 offset:50176
	ds_read_b128 v[206:209], v179 offset:51200
	ds_read_b128 v[210:213], v179 offset:52224
	ds_read_b128 v[214:217], v179 offset:53248
	ds_read_b128 v[218:221], v179 offset:54272
	ds_read_b128 v[222:225], v179 offset:55296
	ds_read_b128 v[226:229], v179 offset:56320
	global_load_lds_dwordx4 v[158:159], off
	s_add_i32 m0, s36, 0x2000
	s_add_u32 s8, s8, 0x40080
	v_lshl_add_u64 v[158:159], v[230:231], 0, s[14:15]
	s_addc_u32 s9, s9, 0
	s_add_i32 s36, s41, s61
	global_load_lds_dwordx4 v[158:159], off
	s_mov_b32 m0, s36
	v_lshl_add_u64 v[158:159], s[8:9], 0, v[134:135]
	global_load_lds_dwordx4 v[158:159], off
	s_add_i32 m0, s36, 0x2000
	v_lshl_add_u64 v[158:159], s[8:9], 0, v[138:139]
	global_load_lds_dwordx4 v[158:159], off
	s_mov_b32 m0, s76
	v_lshl_add_u64 v[158:159], v[232:233], 0, s[14:15]
	global_load_lds_dwordx4 v[158:159], off
	s_mov_b32 m0, s77
	v_lshl_add_u64 v[158:159], v[234:235], 0, s[14:15]
	global_load_lds_dwordx4 v[158:159], off
	s_waitcnt vmcnt(8) lgkmcnt(0)
	s_barrier
	v_mfma_f32_16x16x32_bf16 v[60:63], v[128:131], v[198:201], v[60:63]
	v_mfma_f32_16x16x32_bf16 v[56:59], v[162:165], v[198:201], v[56:59]
	v_mfma_f32_16x16x32_bf16 v[44:47], v[128:131], v[206:209], v[44:47]
	v_mfma_f32_16x16x32_bf16 v[40:43], v[162:165], v[206:209], v[40:43]
	v_mfma_f32_16x16x32_bf16 v[28:31], v[128:131], v[214:217], v[28:31]
	v_mfma_f32_16x16x32_bf16 v[24:27], v[162:165], v[214:217], v[24:27]
	v_mfma_f32_16x16x32_bf16 v[12:15], v[128:131], v[222:225], v[12:15]
	v_mfma_f32_16x16x32_bf16 v[8:11], v[162:165], v[222:225], v[8:11]
	v_mfma_f32_16x16x32_bf16 v[60:63], v[154:157], v[202:205], v[60:63]
	v_mfma_f32_16x16x32_bf16 v[56:59], v[166:169], v[202:205], v[56:59]
	v_mfma_f32_16x16x32_bf16 v[44:47], v[154:157], v[210:213], v[44:47]
	v_mfma_f32_16x16x32_bf16 v[40:43], v[166:169], v[210:213], v[40:43]
	v_mfma_f32_16x16x32_bf16 v[28:31], v[154:157], v[218:221], v[28:31]
	v_mfma_f32_16x16x32_bf16 v[24:27], v[166:169], v[218:221], v[24:27]
	v_mfma_f32_16x16x32_bf16 v[12:15], v[154:157], v[226:229], v[12:15]
	v_mfma_f32_16x16x32_bf16 v[8:11], v[166:169], v[226:229], v[8:11]
	v_mfma_f32_16x16x32_bf16 v[52:55], v[182:185], v[198:201], v[52:55]
	v_mfma_f32_16x16x32_bf16 v[48:51], v[190:193], v[198:201], v[48:51]
	v_mfma_f32_16x16x32_bf16 v[36:39], v[182:185], v[206:209], v[36:39]
	v_mfma_f32_16x16x32_bf16 v[32:35], v[190:193], v[206:209], v[32:35]
	v_mfma_f32_16x16x32_bf16 v[20:23], v[182:185], v[214:217], v[20:23]
	v_mfma_f32_16x16x32_bf16 v[16:19], v[190:193], v[214:217], v[16:19]
	v_mfma_f32_16x16x32_bf16 v[4:7], v[182:185], v[222:225], v[4:7]
	v_mfma_f32_16x16x32_bf16 v[0:3], v[190:193], v[222:225], v[0:3]
	v_mfma_f32_16x16x32_bf16 v[52:55], v[186:189], v[202:205], v[52:55]
	v_mfma_f32_16x16x32_bf16 v[48:51], v[194:197], v[202:205], v[48:51]
	v_mfma_f32_16x16x32_bf16 v[36:39], v[186:189], v[210:213], v[36:39]
	v_mfma_f32_16x16x32_bf16 v[32:35], v[194:197], v[210:213], v[32:35]
	v_mfma_f32_16x16x32_bf16 v[20:23], v[186:189], v[218:221], v[20:23]
	v_mfma_f32_16x16x32_bf16 v[16:19], v[194:197], v[218:221], v[16:19]
	v_mfma_f32_16x16x32_bf16 v[4:7], v[186:189], v[226:229], v[4:7]
	v_mfma_f32_16x16x32_bf16 v[0:3], v[194:197], v[226:229], v[0:3]
	s_barrier
	s_add_i32 s39, s39, 2
	s_add_u32 s0, s0, 0x100
	s_addc_u32 s1, s1, 0
	s_add_u32 s33, s33, 0x100
	s_addc_u32 s38, s38, 0
	s_cmp_gt_u32 s39, 13
	s_cbranch_scc0 .LBB0_799
	s_branch .Lpeel_exit_5

.LBB0_802:
	s_ashr_i32 s50, s6, 2
	s_ashr_i32 s51, s50, 31
	s_lshl_b32 s3, s6, 8
	s_lshl_b64 s[0:1], s[50:51], 28
	s_add_u32 s36, s54, s0
	s_addc_u32 s37, s55, s1
	s_lshl_b32 s27, s2, 8
	s_add_i32 s29, s27, s67
	v_or_b32_e32 v154, s29, v170
	v_ashrrev_i32_e32 v155, 31, v154
	v_lshl_add_u64 v[128:129], v[154:155], 2, s[10:11]
	v_mov_b32_e32 v164, v240
	v_add_u32_e32 v130, 0x80, v154
	v_add_u32_e32 v156, 0x90, v154
	v_add_u32_e32 v158, 0xa0, v154
	v_add_u32_e32 v162, 0xb0, v154
	v_ashrrev_i32_e32 v131, 31, v130
	v_ashrrev_i32_e32 v157, 31, v156
	v_ashrrev_i32_e32 v159, 31, v158
	v_ashrrev_i32_e32 v163, 31, v162
	v_lshl_add_u64 v[130:131], v[130:131], 2, s[10:11]
	v_lshl_add_u64 v[156:157], v[156:157], 2, s[10:11]
	v_lshl_add_u64 v[158:159], v[158:159], 2, s[10:11]
	v_lshl_add_u64 v[162:163], v[162:163], 2, s[10:11]
	v_mov_b32_e32 v188, v241
	v_mov_b32_e32 v187, v242
	v_mov_b32_e32 v186, v243
	v_mov_b32_e32 v185, v244
	v_mov_b32_e32 v184, v245
	v_mov_b32_e32 v183, v246
	v_mov_b32_e32 v182, v247
	s_mul_i32 s1, s50, 0x8100000
	s_and_b32 s3, s3, 0x300
	s_mul_hi_i32 s0, s50, 0x8100000
	s_add_u32 s38, s92, s1
	s_mul_i32 s6, s50, 0x1100000
	s_addc_u32 s39, s93, s0
	v_readlane_b32 s0, v238, 9
	s_mul_hi_i32 s2, s50, 0x1100000
	v_add_u32_e32 v140, 0xffff0000, v154
	v_readlane_b32 s1, v238, 10
	s_add_u32 s40, s0, s6
	v_lshlrev_b64 v[128:129], 11, v[154:155]
	v_lshrrev_b32_e32 v158, 5, v140
	s_addc_u32 s41, s1, s2
	s_lshl_b64 s[0:1], s[50:51], 20
	v_or_b32_e32 v181, s3, v172
	v_lshl_add_u64 v[166:167], s[38:39], 0, v[128:129]
	v_mad_u64_u32 v[128:129], s[2:3], v158, s86, v[142:143]
	s_add_u32 s42, s52, s0
	v_lshlrev_b64 v[156:157], 12, v[154:155]
	v_lshlrev_b64 v[128:129], 11, v[128:129]
	s_addc_u32 s43, s53, s1
	v_lshl_add_u64 v[162:163], s[36:37], 0, v[156:157]
	v_lshl_add_u64 v[156:157], s[40:41], 0, v[128:129]
	s_add_u32 s2, s74, s0
	s_addc_u32 s3, s75, s1
	s_cmp_lt_i32 s50, 2
	s_cselect_b64 s[48:49], -1, 0
	s_cmp_lt_u32 s29, 0x10100
	s_cselect_b64 s[0:1], -1, 0
	s_cmp_gt_u32 s29, 0x100ff
	v_lshlrev_b64 v[130:131], 12, v[140:141]
	v_lshlrev_b32_e32 v140, 1, v181
	s_cselect_b64 s[46:47], -1, 0
	s_cmp_lt_u32 s29, 0x10110
	v_cmp_lt_i32_e64 s[8:9], s85, v154
	v_add_u32_e32 v189, 0xfffeff00, v154
	v_lshl_add_u64 v[158:159], s[42:43], 0, v[130:131]
	s_cselect_b64 s[44:45], -1, 0
	s_cmp_gt_i32 s50, 1
	v_lshl_add_u64 v[166:167], v[166:167], 0, v[140:141]
	v_fmamk_f32 v128, v164, 0x3a800000, v180
	v_rsq_f32_e32 v164, v128
	s_nop 0
	v_pk_mul_f32 v[126:127], v[126:127], v[164:165] op_sel_hi:[1,0]
	v_pk_mul_f32 v[124:125], v[124:125], v[164:165] op_sel_hi:[1,0]
	v_pk_mul_f32 v[122:123], v[122:123], v[164:165] op_sel_hi:[1,0]
	v_pk_mul_f32 v[120:121], v[120:121], v[164:165] op_sel_hi:[1,0]
	v_cvt_pk_bf16_f32 v128, v124, v125
	v_cvt_pk_bf16_f32 v129, v126, v127
	v_cvt_pk_bf16_f32 v130, v120, v121
	v_cvt_pk_bf16_f32 v131, v122, v123
	global_store_dwordx4 v[166:167], v[128:131], off
	s_cbranch_scc1 .LBB0_814
	s_and_saveexec_b64 s[6:7], s[8:9]
	s_xor_b64 s[6:7], exec, s[6:7]
	s_cbranch_execz .LBB0_811
	s_mov_b64 s[50:51], -1
	s_and_b64 vcc, exec, s[46:47]
	s_cbranch_vccz .LBB0_809
	s_andn2_b64 vcc, exec, s[44:45]
	s_cbranch_vccnz .LBB0_808
	v_lshlrev_b32_e32 v168, 2, v181
	v_mov_b32_e32 v169, v141
	v_lshl_add_u64 v[168:169], s[2:3], 0, v[168:169]
	s_mov_b32 s33, 0
